# attention loop: QK MFMAs interleaved 1:1 with the PV MFMAs of groups 0-1, softmax VALU spread evenly over all 24 MFMA gaps (2-4 per gap instead of 5 per PV gap and none beside QK)
# speedup vs baseline: 1.0142x; 1.0132x over previous
; template <int KS> __device__ __forceinline__ void pv_ks(f32x16* o, int vb, bf16x8 pa) {
;     const s16x4 l0 = tr_read<v_rd_off(0, KS, 0)>(vb), h0 = tr_read<v_rd_off(0, KS, 1)>(vb), l1 = tr_read<v_rd_off(1, KS, 0)>(vb), h1 = tr_read<v_rd_off(1, KS, 1)>(vb);
;     const s16x4 l2 = tr_read<v_rd_off(2, KS, 0)>(vb), h2 = tr_read<v_rd_off(2, KS, 1)>(vb), l3 = tr_read<v_rd_off(3, KS, 0)>(vb), h3 = tr_read<v_rd_off(3, KS, 1)>(vb);
;     ...
;     asm volatile("s_waitcnt lgkmcnt(6)" ::: "memory"); SBAR();
;     o[0] = __builtin_amdgcn_mfma_f32_32x32x16_bf16(pa, PK(l0, h0), o[0], 0, 0, 0);
;     asm volatile("s_waitcnt lgkmcnt(4)" ::: "memory"); SBAR();
;     o[1] = __builtin_amdgcn_mfma_f32_32x32x16_bf16(pa, PK(l1, h1), o[1], 0, 0, 0);
;     asm volatile("s_waitcnt lgkmcnt(2)" ::: "memory"); SBAR();
;     o[2] = __builtin_amdgcn_mfma_f32_32x32x16_bf16(pa, PK(l2, h2), o[2], 0, 0, 0);
;     asm volatile("s_waitcnt lgkmcnt(0)" ::: "memory"); SBAR();
;     o[3] = __builtin_amdgcn_mfma_f32_32x32x16_bf16(pa, PK(l3, h3), o[3], 0, 0, 0);
;     ...
; }
; __device__ __forceinline__ void pv_d0(f32x16* o, int vb, bf16x8 pa0, bf16x8 pa1, bf16x8 pa2, bf16x8 pa3) {
;     __builtin_amdgcn_s_setprio(1);
;     pv_ks<0>(o, vb, pa0); pv_ks<1>(o, vb, pa1); pv_ks<2>(o, vb, pa2); pv_ks<3>(o, vb, pa3);
;     __builtin_amdgcn_s_setprio(0);
; }
; __device__ __forceinline__ void exp_half(f32x16& p) {
; #pragma unroll
;     for (int r = 0; r < 16; ++r) p[r] = __builtin_amdgcn_exp2f(p[r]);
; }
; __device__ __forceinline__ void pack_p(const f32x16& p0, const f32x16& p1, float& l_reg, bf16x8& pa0, bf16x8& pa1, bf16x8& pa2, bf16x8& pa3) {
;     float ps = 0;
; #pragma unroll
;     for (int r = 0; r < 16; ++r) ps += p0[r];
; #pragma unroll
;     for (int r = 0; r < 16; ++r) ps += p1[r];
;     l_reg += ps;
;     ...
;     PK4(p0, 0, pa0); PK4(p0, 8, pa1); PK4(p1, 0, pa2); PK4(p1, 8, pa3);
;     ...
; }
; template <int ND0> __device__ __forceinline__ void qkt(f32x16& p0, f32x16& p1, const char* Ks, const bf16x8* qr, int r32, int hi, int colB0) {
; #pragma unroll
;     for (int d0 = 0; d0 < ND0; ++d0) { const int cb = colB0 + (d0 * 16 + hi * 8) * 2;
;         const bf16x8 b0 = *reinterpret_cast<const bf16x8*>(Ks + KSWZ(r32, cb));
;         const bf16x8 b1 = *reinterpret_cast<const bf16x8*>(Ks + KSWZ(32 + r32, cb));
;         p0 = __builtin_amdgcn_mfma_f32_32x32x16_bf16(b0, qr[d0], p0, 0, 0, 0);
.Lsym_biasdone_s0:
	s_add_i32 s55, s55, 64
	v_add_f32_e32 v183, 0xc2800000, v183
	ds_read_b64_tr_b16 v[144:145], v252 offset:0
	ds_read_b64_tr_b16 v[146:147], v252 offset:2048
	ds_read_b64_tr_b16 v[148:149], v252 offset:512
	ds_read_b64_tr_b16 v[150:151], v252 offset:2560
	ds_read_b64_tr_b16 v[152:153], v252 offset:1024
	ds_read_b64_tr_b16 v[154:155], v252 offset:3072
	ds_read_b64_tr_b16 v[156:157], v252 offset:1536
	ds_read_b64_tr_b16 v[158:159], v252 offset:3584
	s_waitcnt lgkmcnt(4)
	v_mfma_f32_32x32x16_bf16 v[48:63], v[128:131], v[144:147], v[48:63]
	ds_read_b64_tr_b16 v[144:145], v252 offset:4096
	ds_read_b64_tr_b16 v[146:147], v252 offset:6144
	v_exp_f32_e32 v88, v88
	v_exp_f32_e32 v89, v89
	v_exp_f32_e32 v90, v90
	v_mfma_f32_32x32x16_bf16 v[112:127], v[192:195], v[172:175], v[112:127]
	v_exp_f32_e32 v91, v91
	v_add_f32_e32 v182, v88, v182
	v_mfma_f32_32x32x16_bf16 v[32:47], v[128:131], v[148:151], v[32:47]
	ds_read_b64_tr_b16 v[148:149], v252 offset:4608
	ds_read_b64_tr_b16 v[150:151], v252 offset:6656
	v_add_f32_e32 v182, v89, v182
	v_cvt_pk_bf16_f32 v132, v88, v89
	v_exp_f32_e32 v92, v92
	v_mfma_f32_32x32x16_bf16 v[96:111], v[196:199], v[172:175], v[96:111]
	v_exp_f32_e32 v93, v93
	v_add_f32_e32 v182, v90, v182
	s_waitcnt lgkmcnt(4)
	v_mfma_f32_32x32x16_bf16 v[16:31], v[128:131], v[152:155], v[16:31]
	ds_read_b64_tr_b16 v[152:153], v252 offset:5120
	ds_read_b64_tr_b16 v[154:155], v252 offset:7168
	v_add_f32_e32 v182, v91, v182
	v_cvt_pk_bf16_f32 v133, v90, v91
	v_exp_f32_e32 v94, v94
	v_mfma_f32_32x32x16_bf16 v[112:127], v[200:203], v[168:171], v[112:127]
	v_exp_f32_e32 v95, v95
	v_add_f32_e32 v182, v92, v182
	v_mfma_f32_32x32x16_bf16 v[0:15], v[128:131], v[156:159], v[0:15]
	ds_read_b64_tr_b16 v[156:157], v252 offset:5632
	ds_read_b64_tr_b16 v[158:159], v252 offset:7680
	v_add_f32_e32 v182, v93, v182
	v_cvt_pk_bf16_f32 v134, v92, v93
	v_cvt_pk_bf16_f32 v135, v94, v95
	v_mfma_f32_32x32x16_bf16 v[96:111], v[204:207], v[168:171], v[96:111]
	v_add_f32_e32 v182, v94, v182
	v_add_f32_e32 v182, v95, v182
	s_waitcnt lgkmcnt(4)
	v_mfma_f32_32x32x16_bf16 v[48:63], v[132:135], v[144:147], v[48:63]
	ds_read_b64_tr_b16 v[144:145], v252 offset:8192
	ds_read_b64_tr_b16 v[146:147], v252 offset:10240
	v_exp_f32_e32 v64, v64
	v_exp_f32_e32 v65, v65
	v_exp_f32_e32 v66, v66
	v_exp_f32_e32 v67, v67
	v_mfma_f32_32x32x16_bf16 v[112:127], v[208:211], v[164:167], v[112:127]
	v_add_f32_e32 v182, v64, v182
	v_add_f32_e32 v182, v65, v182
	v_cvt_pk_bf16_f32 v136, v64, v65
	v_mfma_f32_32x32x16_bf16 v[32:47], v[132:135], v[148:151], v[32:47]
	ds_read_b64_tr_b16 v[148:149], v252 offset:8704
	ds_read_b64_tr_b16 v[150:151], v252 offset:10752
	v_exp_f32_e32 v68, v68
	v_exp_f32_e32 v69, v69
	v_add_f32_e32 v182, v66, v182
	v_add_f32_e32 v182, v67, v182
	v_mfma_f32_32x32x16_bf16 v[96:111], v[212:215], v[164:167], v[96:111]
	v_cvt_pk_bf16_f32 v137, v66, v67
	v_exp_f32_e32 v70, v70
	v_exp_f32_e32 v71, v71
	s_waitcnt lgkmcnt(4)
	v_mfma_f32_32x32x16_bf16 v[16:31], v[132:135], v[152:155], v[16:31]
	ds_read_b64_tr_b16 v[152:153], v252 offset:9216
	ds_read_b64_tr_b16 v[154:155], v252 offset:11264
	v_add_f32_e32 v182, v68, v182
	v_add_f32_e32 v182, v69, v182
	v_cvt_pk_bf16_f32 v138, v68, v69
	v_cvt_pk_bf16_f32 v139, v70, v71
	v_mfma_f32_32x32x16_bf16 v[112:127], v[216:219], v[160:163], v[112:127]
	v_add_f32_e32 v182, v70, v182
	v_add_f32_e32 v182, v71, v182
	v_exp_f32_e32 v72, v72
	v_mfma_f32_32x32x16_bf16 v[0:15], v[132:135], v[156:159], v[0:15]
	ds_read_b64_tr_b16 v[156:157], v252 offset:9728
	ds_read_b64_tr_b16 v[158:159], v252 offset:11776
	v_exp_f32_e32 v73, v73
	v_exp_f32_e32 v74, v74
	v_exp_f32_e32 v75, v75
	v_add_f32_e32 v182, v72, v182
	v_mfma_f32_32x32x16_bf16 v[96:111], v[220:223], v[160:163], v[96:111]
	v_add_f32_e32 v182, v73, v182
	v_cvt_pk_bf16_f32 v140, v72, v73
	v_exp_f32_e32 v76, v76
	s_waitcnt lgkmcnt(4)
	v_mfma_f32_32x32x16_bf16 v[48:63], v[136:139], v[144:147], v[48:63]
	ds_read_b64_tr_b16 v[144:145], v252 offset:12288
	ds_read_b64_tr_b16 v[146:147], v252 offset:14336
	v_exp_f32_e32 v77, v77
	v_add_f32_e32 v182, v74, v182
	v_add_f32_e32 v182, v75, v182
	v_cvt_pk_bf16_f32 v141, v74, v75
	v_mfma_f32_32x32x16_bf16 v[32:47], v[136:139], v[148:151], v[32:47]
	ds_read_b64_tr_b16 v[148:149], v252 offset:12800
	ds_read_b64_tr_b16 v[150:151], v252 offset:14848
	v_exp_f32_e32 v78, v78
	v_exp_f32_e32 v79, v79
	v_add_f32_e32 v182, v76, v182
	v_add_f32_e32 v182, v77, v182
	s_waitcnt lgkmcnt(4)
	v_mfma_f32_32x32x16_bf16 v[16:31], v[136:139], v[152:155], v[16:31]
	ds_read_b64_tr_b16 v[152:153], v252 offset:13312
	ds_read_b64_tr_b16 v[154:155], v252 offset:15360
	v_cvt_pk_bf16_f32 v142, v76, v77
	v_cvt_pk_bf16_f32 v143, v78, v79
	v_add_f32_e32 v182, v78, v182
	v_add_f32_e32 v182, v79, v182
	v_mfma_f32_32x32x16_bf16 v[0:15], v[136:139], v[156:159], v[0:15]
	ds_read_b64_tr_b16 v[156:157], v252 offset:13824
	ds_read_b64_tr_b16 v[158:159], v252 offset:15872
	v_exp_f32_e32 v112, v112
	v_exp_f32_e32 v113, v113
	v_exp_f32_e32 v114, v114
	v_exp_f32_e32 v115, v115
	s_waitcnt lgkmcnt(4)
	v_mfma_f32_32x32x16_bf16 v[48:63], v[140:143], v[144:147], v[48:63]
	v_add_f32_e32 v182, v112, v182
	v_add_f32_e32 v182, v113, v182
	v_cvt_pk_bf16_f32 v128, v112, v113
	v_exp_f32_e32 v116, v116
	v_mfma_f32_32x32x16_bf16 v[32:47], v[140:143], v[148:151], v[32:47]
	v_exp_f32_e32 v117, v117
	v_add_f32_e32 v182, v114, v182
	v_add_f32_e32 v182, v115, v182
	v_cvt_pk_bf16_f32 v129, v114, v115
	s_waitcnt lgkmcnt(0)
	v_mfma_f32_32x32x16_bf16 v[16:31], v[140:143], v[152:155], v[16:31]
	v_exp_f32_e32 v118, v118
	v_exp_f32_e32 v119, v119
	v_add_f32_e32 v182, v116, v182
	v_add_f32_e32 v182, v117, v182
	v_mfma_f32_32x32x16_bf16 v[0:15], v[140:143], v[156:159], v[0:15]
	v_cvt_pk_bf16_f32 v130, v116, v117
	v_cvt_pk_bf16_f32 v131, v118, v119
	v_add_f32_e32 v182, v118, v182
	v_add_f32_e32 v182, v119, v182
	s_add_i32 s54, s54, 1
	s_cmp_ge_i32 s54, s62
	s_cbranch_scc1 .Lsym_last1
	s_waitcnt vmcnt(0)
	s_barrier
	ds_read_b128 v[192:195], v178 offset:32768
	ds_read_b128 v[196:199], v178 offset:40960
	ds_read_b128 v[200:203], v179 offset:32768
	ds_read_b128 v[204:207], v179 offset:40960
	ds_read_b128 v[208:211], v180 offset:32768
	ds_read_b128 v[212:215], v180 offset:40960
	ds_read_b128 v[216:219], v181 offset:32768
	ds_read_b128 v[220:223], v181 offset:40960
	s_add_i32 s53, s54, 2
	s_cmp_le_i32 s53, s62
	s_cbranch_scc0 .Lsym_nostage_s1
	s_add_i32 m0, s25, 0xc000
	s_add_u32 s60, s56, 0x70000
	s_addc_u32 s61, s57, 0
	global_load_lds_dwordx4 v176, s[56:57]
	s_add_i32 m0, s24, 0xc000
	s_nop 0
	global_load_lds_dwordx4 v188, s[56:57]
	s_add_i32 m0, s25, 0xe000
	s_add_u32 s56, s56, 0xe0000
	s_addc_u32 s57, s57, 0
	global_load_lds_dwordx4 v176, s[60:61]
	s_add_i32 m0, s24, 0xe000
	s_nop 0
	global_load_lds_dwordx4 v188, s[60:61]

; template <int KS> __device__ __forceinline__ void pv_ks(f32x16* o, int vb, bf16x8 pa) {
;     const s16x4 l0 = tr_read<v_rd_off(0, KS, 0)>(vb), h0 = tr_read<v_rd_off(0, KS, 1)>(vb), l1 = tr_read<v_rd_off(1, KS, 0)>(vb), h1 = tr_read<v_rd_off(1, KS, 1)>(vb);
;     const s16x4 l2 = tr_read<v_rd_off(2, KS, 0)>(vb), h2 = tr_read<v_rd_off(2, KS, 1)>(vb), l3 = tr_read<v_rd_off(3, KS, 0)>(vb), h3 = tr_read<v_rd_off(3, KS, 1)>(vb);
;     ...
;     asm volatile("s_waitcnt lgkmcnt(6)" ::: "memory"); SBAR();
;     o[0] = __builtin_amdgcn_mfma_f32_32x32x16_bf16(pa, PK(l0, h0), o[0], 0, 0, 0);
;     asm volatile("s_waitcnt lgkmcnt(4)" ::: "memory"); SBAR();
;     o[1] = __builtin_amdgcn_mfma_f32_32x32x16_bf16(pa, PK(l1, h1), o[1], 0, 0, 0);
;     asm volatile("s_waitcnt lgkmcnt(2)" ::: "memory"); SBAR();
;     o[2] = __builtin_amdgcn_mfma_f32_32x32x16_bf16(pa, PK(l2, h2), o[2], 0, 0, 0);
;     asm volatile("s_waitcnt lgkmcnt(0)" ::: "memory"); SBAR();
;     o[3] = __builtin_amdgcn_mfma_f32_32x32x16_bf16(pa, PK(l3, h3), o[3], 0, 0, 0);
;     ...
; }
; __device__ __forceinline__ void pv_d0(f32x16* o, int vb, bf16x8 pa0, bf16x8 pa1, bf16x8 pa2, bf16x8 pa3) {
;     __builtin_amdgcn_s_setprio(1);
;     pv_ks<0>(o, vb, pa0); pv_ks<1>(o, vb, pa1); pv_ks<2>(o, vb, pa2); pv_ks<3>(o, vb, pa3);
;     __builtin_amdgcn_s_setprio(0);
; }
; __device__ __forceinline__ void exp_half(f32x16& p) {
; #pragma unroll
;     for (int r = 0; r < 16; ++r) p[r] = __builtin_amdgcn_exp2f(p[r]);
; }
; __device__ __forceinline__ void pack_p(const f32x16& p0, const f32x16& p1, float& l_reg, bf16x8& pa0, bf16x8& pa1, bf16x8& pa2, bf16x8& pa3) {
;     float ps = 0;
; #pragma unroll
;     for (int r = 0; r < 16; ++r) ps += p0[r];
; #pragma unroll
;     for (int r = 0; r < 16; ++r) ps += p1[r];
;     l_reg += ps;
;     ...
;     PK4(p0, 0, pa0); PK4(p0, 8, pa1); PK4(p1, 0, pa2); PK4(p1, 8, pa3);
;     ...
; }
; template <int ND0> __device__ __forceinline__ void qkt(f32x16& p0, f32x16& p1, const char* Ks, const bf16x8* qr, int r32, int hi, int colB0) {
; #pragma unroll
;     for (int d0 = 0; d0 < ND0; ++d0) { const int cb = colB0 + (d0 * 16 + hi * 8) * 2;
;         const bf16x8 b0 = *reinterpret_cast<const bf16x8*>(Ks + KSWZ(r32, cb));
;         const bf16x8 b1 = *reinterpret_cast<const bf16x8*>(Ks + KSWZ(32 + r32, cb));
;         p0 = __builtin_amdgcn_mfma_f32_32x32x16_bf16(b0, qr[d0], p0, 0, 0, 0);
.Lsym_biasdone_s1:
	s_add_i32 s55, s55, 64
	v_add_f32_e32 v183, 0xc2800000, v183
	ds_read_b64_tr_b16 v[144:145], v252 offset:16384
	ds_read_b64_tr_b16 v[146:147], v252 offset:18432
	ds_read_b64_tr_b16 v[148:149], v252 offset:16896
	ds_read_b64_tr_b16 v[150:151], v252 offset:18944
	ds_read_b64_tr_b16 v[152:153], v252 offset:17408
	ds_read_b64_tr_b16 v[154:155], v252 offset:19456
	ds_read_b64_tr_b16 v[156:157], v252 offset:17920
	ds_read_b64_tr_b16 v[158:159], v252 offset:19968
	s_waitcnt lgkmcnt(4)
	v_mfma_f32_32x32x16_bf16 v[48:63], v[128:131], v[144:147], v[48:63]
	ds_read_b64_tr_b16 v[144:145], v252 offset:20480
	ds_read_b64_tr_b16 v[146:147], v252 offset:22528
	v_exp_f32_e32 v120, v120
	v_exp_f32_e32 v121, v121
	v_exp_f32_e32 v122, v122
	v_mfma_f32_32x32x16_bf16 v[80:95], v[192:195], v[172:175], v[80:95]
	v_exp_f32_e32 v123, v123
	v_add_f32_e32 v182, v120, v182
	v_mfma_f32_32x32x16_bf16 v[32:47], v[128:131], v[148:151], v[32:47]
	ds_read_b64_tr_b16 v[148:149], v252 offset:20992
	ds_read_b64_tr_b16 v[150:151], v252 offset:23040
	v_add_f32_e32 v182, v121, v182
	v_cvt_pk_bf16_f32 v132, v120, v121
	v_exp_f32_e32 v124, v124
	v_mfma_f32_32x32x16_bf16 v[64:79], v[196:199], v[172:175], v[64:79]
	v_exp_f32_e32 v125, v125
	v_add_f32_e32 v182, v122, v182
	s_waitcnt lgkmcnt(4)
	v_mfma_f32_32x32x16_bf16 v[16:31], v[128:131], v[152:155], v[16:31]
	ds_read_b64_tr_b16 v[152:153], v252 offset:21504
	ds_read_b64_tr_b16 v[154:155], v252 offset:23552
	v_add_f32_e32 v182, v123, v182
	v_cvt_pk_bf16_f32 v133, v122, v123
	v_exp_f32_e32 v126, v126
	v_mfma_f32_32x32x16_bf16 v[80:95], v[200:203], v[168:171], v[80:95]
	v_exp_f32_e32 v127, v127
	v_add_f32_e32 v182, v124, v182
	v_mfma_f32_32x32x16_bf16 v[0:15], v[128:131], v[156:159], v[0:15]
	ds_read_b64_tr_b16 v[156:157], v252 offset:22016
	ds_read_b64_tr_b16 v[158:159], v252 offset:24064
	v_add_f32_e32 v182, v125, v182
	v_cvt_pk_bf16_f32 v134, v124, v125
	v_cvt_pk_bf16_f32 v135, v126, v127
	v_mfma_f32_32x32x16_bf16 v[64:79], v[204:207], v[168:171], v[64:79]
	v_add_f32_e32 v182, v126, v182
	v_add_f32_e32 v182, v127, v182
	s_waitcnt lgkmcnt(4)
	v_mfma_f32_32x32x16_bf16 v[48:63], v[132:135], v[144:147], v[48:63]
	ds_read_b64_tr_b16 v[144:145], v252 offset:24576
	ds_read_b64_tr_b16 v[146:147], v252 offset:26624
	v_exp_f32_e32 v96, v96
	v_exp_f32_e32 v97, v97
	v_exp_f32_e32 v98, v98
	v_exp_f32_e32 v99, v99
	v_mfma_f32_32x32x16_bf16 v[80:95], v[208:211], v[164:167], v[80:95]
	v_add_f32_e32 v182, v96, v182
	v_add_f32_e32 v182, v97, v182
	v_cvt_pk_bf16_f32 v136, v96, v97
	v_mfma_f32_32x32x16_bf16 v[32:47], v[132:135], v[148:151], v[32:47]
	ds_read_b64_tr_b16 v[148:149], v252 offset:25088
	ds_read_b64_tr_b16 v[150:151], v252 offset:27136
	v_exp_f32_e32 v100, v100
	v_exp_f32_e32 v101, v101
	v_add_f32_e32 v182, v98, v182
	v_add_f32_e32 v182, v99, v182
	v_mfma_f32_32x32x16_bf16 v[64:79], v[212:215], v[164:167], v[64:79]
	v_cvt_pk_bf16_f32 v137, v98, v99
	v_exp_f32_e32 v102, v102
	v_exp_f32_e32 v103, v103
	s_waitcnt lgkmcnt(4)
	v_mfma_f32_32x32x16_bf16 v[16:31], v[132:135], v[152:155], v[16:31]
	ds_read_b64_tr_b16 v[152:153], v252 offset:25600
	ds_read_b64_tr_b16 v[154:155], v252 offset:27648
	v_add_f32_e32 v182, v100, v182
	v_add_f32_e32 v182, v101, v182
	v_cvt_pk_bf16_f32 v138, v100, v101
	v_cvt_pk_bf16_f32 v139, v102, v103
	v_mfma_f32_32x32x16_bf16 v[80:95], v[216:219], v[160:163], v[80:95]
	v_add_f32_e32 v182, v102, v182
	v_add_f32_e32 v182, v103, v182
	v_exp_f32_e32 v104, v104
	v_mfma_f32_32x32x16_bf16 v[0:15], v[132:135], v[156:159], v[0:15]
	ds_read_b64_tr_b16 v[156:157], v252 offset:26112
	ds_read_b64_tr_b16 v[158:159], v252 offset:28160
	v_exp_f32_e32 v105, v105
	v_exp_f32_e32 v106, v106
	v_exp_f32_e32 v107, v107
	v_add_f32_e32 v182, v104, v182
	v_mfma_f32_32x32x16_bf16 v[64:79], v[220:223], v[160:163], v[64:79]
	v_add_f32_e32 v182, v105, v182
	v_cvt_pk_bf16_f32 v140, v104, v105
	v_exp_f32_e32 v108, v108
	s_waitcnt lgkmcnt(4)
	v_mfma_f32_32x32x16_bf16 v[48:63], v[136:139], v[144:147], v[48:63]
	ds_read_b64_tr_b16 v[144:145], v252 offset:28672
	ds_read_b64_tr_b16 v[146:147], v252 offset:30720
	v_exp_f32_e32 v109, v109
	v_add_f32_e32 v182, v106, v182
	v_add_f32_e32 v182, v107, v182
	v_cvt_pk_bf16_f32 v141, v106, v107
	v_mfma_f32_32x32x16_bf16 v[32:47], v[136:139], v[148:151], v[32:47]
	ds_read_b64_tr_b16 v[148:149], v252 offset:29184
	ds_read_b64_tr_b16 v[150:151], v252 offset:31232
	v_exp_f32_e32 v110, v110
	v_exp_f32_e32 v111, v111
	v_add_f32_e32 v182, v108, v182
	v_add_f32_e32 v182, v109, v182
	s_waitcnt lgkmcnt(4)
	v_mfma_f32_32x32x16_bf16 v[16:31], v[136:139], v[152:155], v[16:31]
	ds_read_b64_tr_b16 v[152:153], v252 offset:29696
	ds_read_b64_tr_b16 v[154:155], v252 offset:31744
	v_cvt_pk_bf16_f32 v142, v108, v109
	v_cvt_pk_bf16_f32 v143, v110, v111
	v_add_f32_e32 v182, v110, v182
	v_add_f32_e32 v182, v111, v182
	v_mfma_f32_32x32x16_bf16 v[0:15], v[136:139], v[156:159], v[0:15]
	ds_read_b64_tr_b16 v[156:157], v252 offset:30208
	ds_read_b64_tr_b16 v[158:159], v252 offset:32256
	v_exp_f32_e32 v80, v80
	v_exp_f32_e32 v81, v81
	v_exp_f32_e32 v82, v82
	v_exp_f32_e32 v83, v83
	s_waitcnt lgkmcnt(4)
	v_mfma_f32_32x32x16_bf16 v[48:63], v[140:143], v[144:147], v[48:63]
	v_add_f32_e32 v182, v80, v182
	v_add_f32_e32 v182, v81, v182
	v_cvt_pk_bf16_f32 v128, v80, v81
	v_exp_f32_e32 v84, v84
	v_mfma_f32_32x32x16_bf16 v[32:47], v[140:143], v[148:151], v[32:47]
	v_exp_f32_e32 v85, v85
	v_add_f32_e32 v182, v82, v182
	v_add_f32_e32 v182, v83, v182
	v_cvt_pk_bf16_f32 v129, v82, v83
	s_waitcnt lgkmcnt(0)
	v_mfma_f32_32x32x16_bf16 v[16:31], v[140:143], v[152:155], v[16:31]
	v_exp_f32_e32 v86, v86
	v_exp_f32_e32 v87, v87
	v_add_f32_e32 v182, v84, v182
	v_add_f32_e32 v182, v85, v182
	v_mfma_f32_32x32x16_bf16 v[0:15], v[140:143], v[156:159], v[0:15]
	v_cvt_pk_bf16_f32 v130, v84, v85
	v_cvt_pk_bf16_f32 v131, v86, v87
	v_add_f32_e32 v182, v86, v182
	v_add_f32_e32 v182, v87, v182
	s_add_i32 s54, s54, 1
	s_waitcnt vmcnt(0)
	s_barrier
	ds_read_b128 v[192:195], v178 offset:49152
	ds_read_b128 v[196:199], v178 offset:57344
	ds_read_b128 v[200:203], v179 offset:49152
	ds_read_b128 v[204:207], v179 offset:57344
	ds_read_b128 v[208:211], v180 offset:49152
	ds_read_b128 v[212:215], v180 offset:57344
	ds_read_b128 v[216:219], v181 offset:49152
	ds_read_b128 v[220:223], v181 offset:57344
	s_add_i32 s53, s54, 2
	s_cmp_le_i32 s53, s62
	s_cbranch_scc0 .Lsym_nostage_s2
	s_add_i32 m0, s25, 0x0
	s_add_u32 s60, s56, 0x70000
	s_addc_u32 s61, s57, 0
	global_load_lds_dwordx4 v176, s[56:57]
	s_add_i32 m0, s24, 0x0
	s_nop 0
	global_load_lds_dwordx4 v188, s[56:57]
	s_add_i32 m0, s25, 0x2000
	s_add_u32 s56, s56, 0xe0000
	s_addc_u32 s57, s57, 0
	global_load_lds_dwordx4 v176, s[60:61]
	s_add_i32 m0, s24, 0x2000
	s_nop 0
	global_load_lds_dwordx4 v188, s[60:61]

; template <int KS> __device__ __forceinline__ void pv_ks(f32x16* o, int vb, bf16x8 pa) {
;     const s16x4 l0 = tr_read<v_rd_off(0, KS, 0)>(vb), h0 = tr_read<v_rd_off(0, KS, 1)>(vb), l1 = tr_read<v_rd_off(1, KS, 0)>(vb), h1 = tr_read<v_rd_off(1, KS, 1)>(vb);
;     const s16x4 l2 = tr_read<v_rd_off(2, KS, 0)>(vb), h2 = tr_read<v_rd_off(2, KS, 1)>(vb), l3 = tr_read<v_rd_off(3, KS, 0)>(vb), h3 = tr_read<v_rd_off(3, KS, 1)>(vb);
;     ...
;     asm volatile("s_waitcnt lgkmcnt(6)" ::: "memory"); SBAR();
;     o[0] = __builtin_amdgcn_mfma_f32_32x32x16_bf16(pa, PK(l0, h0), o[0], 0, 0, 0);
;     asm volatile("s_waitcnt lgkmcnt(4)" ::: "memory"); SBAR();
;     o[1] = __builtin_amdgcn_mfma_f32_32x32x16_bf16(pa, PK(l1, h1), o[1], 0, 0, 0);
;     asm volatile("s_waitcnt lgkmcnt(2)" ::: "memory"); SBAR();
;     o[2] = __builtin_amdgcn_mfma_f32_32x32x16_bf16(pa, PK(l2, h2), o[2], 0, 0, 0);
;     asm volatile("s_waitcnt lgkmcnt(0)" ::: "memory"); SBAR();
;     o[3] = __builtin_amdgcn_mfma_f32_32x32x16_bf16(pa, PK(l3, h3), o[3], 0, 0, 0);
;     ...
; }
; __device__ __forceinline__ void pv_d0(f32x16* o, int vb, bf16x8 pa0, bf16x8 pa1, bf16x8 pa2, bf16x8 pa3) {
;     __builtin_amdgcn_s_setprio(1);
;     pv_ks<0>(o, vb, pa0); pv_ks<1>(o, vb, pa1); pv_ks<2>(o, vb, pa2); pv_ks<3>(o, vb, pa3);
;     __builtin_amdgcn_s_setprio(0);
; }
; __device__ __forceinline__ void exp_half(f32x16& p) {
; #pragma unroll
;     for (int r = 0; r < 16; ++r) p[r] = __builtin_amdgcn_exp2f(p[r]);
; }
; __device__ __forceinline__ void pack_p(const f32x16& p0, const f32x16& p1, float& l_reg, bf16x8& pa0, bf16x8& pa1, bf16x8& pa2, bf16x8& pa3) {
;     float ps = 0;
; #pragma unroll
;     for (int r = 0; r < 16; ++r) ps += p0[r];
; #pragma unroll
;     for (int r = 0; r < 16; ++r) ps += p1[r];
;     l_reg += ps;
;     ...
;     PK4(p0, 0, pa0); PK4(p0, 8, pa1); PK4(p1, 0, pa2); PK4(p1, 8, pa3);
;     ...
; }
; template <int ND0> __device__ __forceinline__ void qkt(f32x16& p0, f32x16& p1, const char* Ks, const bf16x8* qr, int r32, int hi, int colB0) {
; #pragma unroll
;     for (int d0 = 0; d0 < ND0; ++d0) { const int cb = colB0 + (d0 * 16 + hi * 8) * 2;
;         const bf16x8 b0 = *reinterpret_cast<const bf16x8*>(Ks + KSWZ(r32, cb));
;         const bf16x8 b1 = *reinterpret_cast<const bf16x8*>(Ks + KSWZ(32 + r32, cb));
;         p0 = __builtin_amdgcn_mfma_f32_32x32x16_bf16(b0, qr[d0], p0, 0, 0, 0);
.Lsym_biasdone_s2:
	s_add_i32 s55, s55, 64
	v_add_f32_e32 v183, 0xc2800000, v183
	ds_read_b64_tr_b16 v[144:145], v252 offset:32768
	ds_read_b64_tr_b16 v[146:147], v252 offset:34816
	ds_read_b64_tr_b16 v[148:149], v252 offset:33280
	ds_read_b64_tr_b16 v[150:151], v252 offset:35328
	ds_read_b64_tr_b16 v[152:153], v252 offset:33792
	ds_read_b64_tr_b16 v[154:155], v252 offset:35840
	ds_read_b64_tr_b16 v[156:157], v252 offset:34304
	ds_read_b64_tr_b16 v[158:159], v252 offset:36352
	s_waitcnt lgkmcnt(4)
	v_mfma_f32_32x32x16_bf16 v[48:63], v[128:131], v[144:147], v[48:63]
	ds_read_b64_tr_b16 v[144:145], v252 offset:36864
	ds_read_b64_tr_b16 v[146:147], v252 offset:38912
	v_exp_f32_e32 v88, v88
	v_exp_f32_e32 v89, v89
	v_exp_f32_e32 v90, v90
	v_mfma_f32_32x32x16_bf16 v[112:127], v[192:195], v[172:175], v[112:127]
	v_exp_f32_e32 v91, v91
	v_add_f32_e32 v182, v88, v182
	v_mfma_f32_32x32x16_bf16 v[32:47], v[128:131], v[148:151], v[32:47]
	ds_read_b64_tr_b16 v[148:149], v252 offset:37376
	ds_read_b64_tr_b16 v[150:151], v252 offset:39424
	v_add_f32_e32 v182, v89, v182
	v_cvt_pk_bf16_f32 v132, v88, v89
	v_exp_f32_e32 v92, v92
	v_mfma_f32_32x32x16_bf16 v[96:111], v[196:199], v[172:175], v[96:111]
	v_exp_f32_e32 v93, v93
	v_add_f32_e32 v182, v90, v182
	s_waitcnt lgkmcnt(4)
	v_mfma_f32_32x32x16_bf16 v[16:31], v[128:131], v[152:155], v[16:31]
	ds_read_b64_tr_b16 v[152:153], v252 offset:37888
	ds_read_b64_tr_b16 v[154:155], v252 offset:39936
	v_add_f32_e32 v182, v91, v182
	v_cvt_pk_bf16_f32 v133, v90, v91
	v_exp_f32_e32 v94, v94
	v_mfma_f32_32x32x16_bf16 v[112:127], v[200:203], v[168:171], v[112:127]
	v_exp_f32_e32 v95, v95
	v_add_f32_e32 v182, v92, v182
	v_mfma_f32_32x32x16_bf16 v[0:15], v[128:131], v[156:159], v[0:15]
	ds_read_b64_tr_b16 v[156:157], v252 offset:38400
	ds_read_b64_tr_b16 v[158:159], v252 offset:40448
	v_add_f32_e32 v182, v93, v182
	v_cvt_pk_bf16_f32 v134, v92, v93
	v_cvt_pk_bf16_f32 v135, v94, v95
	v_mfma_f32_32x32x16_bf16 v[96:111], v[204:207], v[168:171], v[96:111]
	v_add_f32_e32 v182, v94, v182
	v_add_f32_e32 v182, v95, v182
	s_waitcnt lgkmcnt(4)
	v_mfma_f32_32x32x16_bf16 v[48:63], v[132:135], v[144:147], v[48:63]
	ds_read_b64_tr_b16 v[144:145], v252 offset:40960
	ds_read_b64_tr_b16 v[146:147], v252 offset:43008
	v_exp_f32_e32 v64, v64
	v_exp_f32_e32 v65, v65
	v_exp_f32_e32 v66, v66
	v_exp_f32_e32 v67, v67
	v_mfma_f32_32x32x16_bf16 v[112:127], v[208:211], v[164:167], v[112:127]
	v_add_f32_e32 v182, v64, v182
	v_add_f32_e32 v182, v65, v182
	v_cvt_pk_bf16_f32 v136, v64, v65
	v_mfma_f32_32x32x16_bf16 v[32:47], v[132:135], v[148:151], v[32:47]
	ds_read_b64_tr_b16 v[148:149], v252 offset:41472
	ds_read_b64_tr_b16 v[150:151], v252 offset:43520
	v_exp_f32_e32 v68, v68
	v_exp_f32_e32 v69, v69
	v_add_f32_e32 v182, v66, v182
	v_add_f32_e32 v182, v67, v182
	v_mfma_f32_32x32x16_bf16 v[96:111], v[212:215], v[164:167], v[96:111]
	v_cvt_pk_bf16_f32 v137, v66, v67
	v_exp_f32_e32 v70, v70
	v_exp_f32_e32 v71, v71
	s_waitcnt lgkmcnt(4)
	v_mfma_f32_32x32x16_bf16 v[16:31], v[132:135], v[152:155], v[16:31]
	ds_read_b64_tr_b16 v[152:153], v252 offset:41984
	ds_read_b64_tr_b16 v[154:155], v252 offset:44032
	v_add_f32_e32 v182, v68, v182
	v_add_f32_e32 v182, v69, v182
	v_cvt_pk_bf16_f32 v138, v68, v69
	v_cvt_pk_bf16_f32 v139, v70, v71
	v_mfma_f32_32x32x16_bf16 v[112:127], v[216:219], v[160:163], v[112:127]
	v_add_f32_e32 v182, v70, v182
	v_add_f32_e32 v182, v71, v182
	v_exp_f32_e32 v72, v72
	v_mfma_f32_32x32x16_bf16 v[0:15], v[132:135], v[156:159], v[0:15]
	ds_read_b64_tr_b16 v[156:157], v252 offset:42496
	ds_read_b64_tr_b16 v[158:159], v252 offset:44544
	v_exp_f32_e32 v73, v73
	v_exp_f32_e32 v74, v74
	v_exp_f32_e32 v75, v75
	v_add_f32_e32 v182, v72, v182
	v_mfma_f32_32x32x16_bf16 v[96:111], v[220:223], v[160:163], v[96:111]
	v_add_f32_e32 v182, v73, v182
	v_cvt_pk_bf16_f32 v140, v72, v73
	v_exp_f32_e32 v76, v76
	s_waitcnt lgkmcnt(4)
	v_mfma_f32_32x32x16_bf16 v[48:63], v[136:139], v[144:147], v[48:63]
	ds_read_b64_tr_b16 v[144:145], v252 offset:45056
	ds_read_b64_tr_b16 v[146:147], v252 offset:47104
	v_exp_f32_e32 v77, v77
	v_add_f32_e32 v182, v74, v182
	v_add_f32_e32 v182, v75, v182
	v_cvt_pk_bf16_f32 v141, v74, v75
	v_mfma_f32_32x32x16_bf16 v[32:47], v[136:139], v[148:151], v[32:47]
	ds_read_b64_tr_b16 v[148:149], v252 offset:45568
	ds_read_b64_tr_b16 v[150:151], v252 offset:47616
	v_exp_f32_e32 v78, v78
	v_exp_f32_e32 v79, v79
	v_add_f32_e32 v182, v76, v182
	v_add_f32_e32 v182, v77, v182
	s_waitcnt lgkmcnt(4)
	v_mfma_f32_32x32x16_bf16 v[16:31], v[136:139], v[152:155], v[16:31]
	ds_read_b64_tr_b16 v[152:153], v252 offset:46080
	ds_read_b64_tr_b16 v[154:155], v252 offset:48128
	v_cvt_pk_bf16_f32 v142, v76, v77
	v_cvt_pk_bf16_f32 v143, v78, v79
	v_add_f32_e32 v182, v78, v182
	v_add_f32_e32 v182, v79, v182
	v_mfma_f32_32x32x16_bf16 v[0:15], v[136:139], v[156:159], v[0:15]
	ds_read_b64_tr_b16 v[156:157], v252 offset:46592
	ds_read_b64_tr_b16 v[158:159], v252 offset:48640
	v_exp_f32_e32 v112, v112
	v_exp_f32_e32 v113, v113
	v_exp_f32_e32 v114, v114
	v_exp_f32_e32 v115, v115
	s_waitcnt lgkmcnt(4)
	v_mfma_f32_32x32x16_bf16 v[48:63], v[140:143], v[144:147], v[48:63]
	v_add_f32_e32 v182, v112, v182
	v_add_f32_e32 v182, v113, v182
	v_cvt_pk_bf16_f32 v128, v112, v113
	v_exp_f32_e32 v116, v116
	v_mfma_f32_32x32x16_bf16 v[32:47], v[140:143], v[148:151], v[32:47]
	v_exp_f32_e32 v117, v117
	v_add_f32_e32 v182, v114, v182
	v_add_f32_e32 v182, v115, v182
	v_cvt_pk_bf16_f32 v129, v114, v115
	s_waitcnt lgkmcnt(0)
	v_mfma_f32_32x32x16_bf16 v[16:31], v[140:143], v[152:155], v[16:31]
	v_exp_f32_e32 v118, v118
	v_exp_f32_e32 v119, v119
	v_add_f32_e32 v182, v116, v182
	v_add_f32_e32 v182, v117, v182
	v_mfma_f32_32x32x16_bf16 v[0:15], v[140:143], v[156:159], v[0:15]
	v_cvt_pk_bf16_f32 v130, v116, v117
	v_cvt_pk_bf16_f32 v131, v118, v119
	v_add_f32_e32 v182, v118, v182
	v_add_f32_e32 v182, v119, v182
	s_add_i32 s54, s54, 1
	s_cmp_ge_i32 s54, s62
	s_cbranch_scc1 .Lsym_last3
	s_waitcnt vmcnt(0)
	s_barrier
	ds_read_b128 v[192:195], v178 offset:0
	ds_read_b128 v[196:199], v178 offset:8192
	ds_read_b128 v[200:203], v179 offset:0
	ds_read_b128 v[204:207], v179 offset:8192
	ds_read_b128 v[208:211], v180 offset:0
	ds_read_b128 v[212:215], v180 offset:8192
	ds_read_b128 v[216:219], v181 offset:0
	ds_read_b128 v[220:223], v181 offset:8192
	s_add_i32 s53, s54, 2
	s_cmp_le_i32 s53, s62
	s_cbranch_scc0 .Lsym_nostage_s3
	s_add_i32 m0, s25, 0x4000
	s_add_u32 s60, s56, 0x70000
	s_addc_u32 s61, s57, 0
	global_load_lds_dwordx4 v176, s[56:57]
	s_add_i32 m0, s24, 0x4000
	s_nop 0
	global_load_lds_dwordx4 v188, s[56:57]
	s_add_i32 m0, s25, 0x6000
	s_add_u32 s56, s56, 0xe0000
	s_addc_u32 s57, s57, 0
	global_load_lds_dwordx4 v176, s[60:61]
	s_add_i32 m0, s24, 0x6000
	s_nop 0
	global_load_lds_dwordx4 v188, s[60:61]

; template <int KS> __device__ __forceinline__ void pv_ks(f32x16* o, int vb, bf16x8 pa) {
;     const s16x4 l0 = tr_read<v_rd_off(0, KS, 0)>(vb), h0 = tr_read<v_rd_off(0, KS, 1)>(vb), l1 = tr_read<v_rd_off(1, KS, 0)>(vb), h1 = tr_read<v_rd_off(1, KS, 1)>(vb);
;     const s16x4 l2 = tr_read<v_rd_off(2, KS, 0)>(vb), h2 = tr_read<v_rd_off(2, KS, 1)>(vb), l3 = tr_read<v_rd_off(3, KS, 0)>(vb), h3 = tr_read<v_rd_off(3, KS, 1)>(vb);
;     ...
;     asm volatile("s_waitcnt lgkmcnt(6)" ::: "memory"); SBAR();
;     o[0] = __builtin_amdgcn_mfma_f32_32x32x16_bf16(pa, PK(l0, h0), o[0], 0, 0, 0);
;     asm volatile("s_waitcnt lgkmcnt(4)" ::: "memory"); SBAR();
;     o[1] = __builtin_amdgcn_mfma_f32_32x32x16_bf16(pa, PK(l1, h1), o[1], 0, 0, 0);
;     asm volatile("s_waitcnt lgkmcnt(2)" ::: "memory"); SBAR();
;     o[2] = __builtin_amdgcn_mfma_f32_32x32x16_bf16(pa, PK(l2, h2), o[2], 0, 0, 0);
;     asm volatile("s_waitcnt lgkmcnt(0)" ::: "memory"); SBAR();
;     o[3] = __builtin_amdgcn_mfma_f32_32x32x16_bf16(pa, PK(l3, h3), o[3], 0, 0, 0);
;     ...
; }
; __device__ __forceinline__ void pv_d0(f32x16* o, int vb, bf16x8 pa0, bf16x8 pa1, bf16x8 pa2, bf16x8 pa3) {
;     __builtin_amdgcn_s_setprio(1);
;     pv_ks<0>(o, vb, pa0); pv_ks<1>(o, vb, pa1); pv_ks<2>(o, vb, pa2); pv_ks<3>(o, vb, pa3);
;     __builtin_amdgcn_s_setprio(0);
; }
; __device__ __forceinline__ void exp_half(f32x16& p) {
; #pragma unroll
;     for (int r = 0; r < 16; ++r) p[r] = __builtin_amdgcn_exp2f(p[r]);
; }
; __device__ __forceinline__ void pack_p(const f32x16& p0, const f32x16& p1, float& l_reg, bf16x8& pa0, bf16x8& pa1, bf16x8& pa2, bf16x8& pa3) {
;     float ps = 0;
; #pragma unroll
;     for (int r = 0; r < 16; ++r) ps += p0[r];
; #pragma unroll
;     for (int r = 0; r < 16; ++r) ps += p1[r];
;     l_reg += ps;
;     ...
;     PK4(p0, 0, pa0); PK4(p0, 8, pa1); PK4(p1, 0, pa2); PK4(p1, 8, pa3);
;     ...
; }
; template <int ND0> __device__ __forceinline__ void qkt(f32x16& p0, f32x16& p1, const char* Ks, const bf16x8* qr, int r32, int hi, int colB0) {
; #pragma unroll
;     for (int d0 = 0; d0 < ND0; ++d0) { const int cb = colB0 + (d0 * 16 + hi * 8) * 2;
;         const bf16x8 b0 = *reinterpret_cast<const bf16x8*>(Ks + KSWZ(r32, cb));
;         const bf16x8 b1 = *reinterpret_cast<const bf16x8*>(Ks + KSWZ(32 + r32, cb));
;         p0 = __builtin_amdgcn_mfma_f32_32x32x16_bf16(b0, qr[d0], p0, 0, 0, 0);
.Lsym_biasdone_s3:
	s_add_i32 s55, s55, 64
	v_add_f32_e32 v183, 0xc2800000, v183
	ds_read_b64_tr_b16 v[144:145], v252 offset:49152
	ds_read_b64_tr_b16 v[146:147], v252 offset:51200
	ds_read_b64_tr_b16 v[148:149], v252 offset:49664
	ds_read_b64_tr_b16 v[150:151], v252 offset:51712
	ds_read_b64_tr_b16 v[152:153], v252 offset:50176
	ds_read_b64_tr_b16 v[154:155], v252 offset:52224
	ds_read_b64_tr_b16 v[156:157], v252 offset:50688
	ds_read_b64_tr_b16 v[158:159], v252 offset:52736
	s_waitcnt lgkmcnt(4)
	v_mfma_f32_32x32x16_bf16 v[48:63], v[128:131], v[144:147], v[48:63]
	ds_read_b64_tr_b16 v[144:145], v252 offset:53248
	ds_read_b64_tr_b16 v[146:147], v252 offset:55296
	v_exp_f32_e32 v120, v120
	v_exp_f32_e32 v121, v121
	v_exp_f32_e32 v122, v122
	v_mfma_f32_32x32x16_bf16 v[80:95], v[192:195], v[172:175], v[80:95]
	v_exp_f32_e32 v123, v123
	v_add_f32_e32 v182, v120, v182
	v_mfma_f32_32x32x16_bf16 v[32:47], v[128:131], v[148:151], v[32:47]
	ds_read_b64_tr_b16 v[148:149], v252 offset:53760
	ds_read_b64_tr_b16 v[150:151], v252 offset:55808
	v_add_f32_e32 v182, v121, v182
	v_cvt_pk_bf16_f32 v132, v120, v121
	v_exp_f32_e32 v124, v124
	v_mfma_f32_32x32x16_bf16 v[64:79], v[196:199], v[172:175], v[64:79]
	v_exp_f32_e32 v125, v125
	v_add_f32_e32 v182, v122, v182
	s_waitcnt lgkmcnt(4)
	v_mfma_f32_32x32x16_bf16 v[16:31], v[128:131], v[152:155], v[16:31]
	ds_read_b64_tr_b16 v[152:153], v252 offset:54272
	ds_read_b64_tr_b16 v[154:155], v252 offset:56320
	v_add_f32_e32 v182, v123, v182
	v_cvt_pk_bf16_f32 v133, v122, v123
	v_exp_f32_e32 v126, v126
	v_mfma_f32_32x32x16_bf16 v[80:95], v[200:203], v[168:171], v[80:95]
	v_exp_f32_e32 v127, v127
	v_add_f32_e32 v182, v124, v182
	v_mfma_f32_32x32x16_bf16 v[0:15], v[128:131], v[156:159], v[0:15]
	ds_read_b64_tr_b16 v[156:157], v252 offset:54784
	ds_read_b64_tr_b16 v[158:159], v252 offset:56832
	v_add_f32_e32 v182, v125, v182
	v_cvt_pk_bf16_f32 v134, v124, v125
	v_cvt_pk_bf16_f32 v135, v126, v127
	v_mfma_f32_32x32x16_bf16 v[64:79], v[204:207], v[168:171], v[64:79]
	v_add_f32_e32 v182, v126, v182
	v_add_f32_e32 v182, v127, v182
	s_waitcnt lgkmcnt(4)
	v_mfma_f32_32x32x16_bf16 v[48:63], v[132:135], v[144:147], v[48:63]
	ds_read_b64_tr_b16 v[144:145], v252 offset:57344
	ds_read_b64_tr_b16 v[146:147], v252 offset:59392
	v_exp_f32_e32 v96, v96
	v_exp_f32_e32 v97, v97
	v_exp_f32_e32 v98, v98
	v_exp_f32_e32 v99, v99
	v_mfma_f32_32x32x16_bf16 v[80:95], v[208:211], v[164:167], v[80:95]
	v_add_f32_e32 v182, v96, v182
	v_add_f32_e32 v182, v97, v182
	v_cvt_pk_bf16_f32 v136, v96, v97
	v_mfma_f32_32x32x16_bf16 v[32:47], v[132:135], v[148:151], v[32:47]
	ds_read_b64_tr_b16 v[148:149], v252 offset:57856
	ds_read_b64_tr_b16 v[150:151], v252 offset:59904
	v_exp_f32_e32 v100, v100
	v_exp_f32_e32 v101, v101
	v_add_f32_e32 v182, v98, v182
	v_add_f32_e32 v182, v99, v182
	v_mfma_f32_32x32x16_bf16 v[64:79], v[212:215], v[164:167], v[64:79]
	v_cvt_pk_bf16_f32 v137, v98, v99
	v_exp_f32_e32 v102, v102
	v_exp_f32_e32 v103, v103
	s_waitcnt lgkmcnt(4)
	v_mfma_f32_32x32x16_bf16 v[16:31], v[132:135], v[152:155], v[16:31]
	ds_read_b64_tr_b16 v[152:153], v252 offset:58368
	ds_read_b64_tr_b16 v[154:155], v252 offset:60416
	v_add_f32_e32 v182, v100, v182
	v_add_f32_e32 v182, v101, v182
	v_cvt_pk_bf16_f32 v138, v100, v101
	v_cvt_pk_bf16_f32 v139, v102, v103
	v_mfma_f32_32x32x16_bf16 v[80:95], v[216:219], v[160:163], v[80:95]
	v_add_f32_e32 v182, v102, v182
	v_add_f32_e32 v182, v103, v182
	v_exp_f32_e32 v104, v104
	v_mfma_f32_32x32x16_bf16 v[0:15], v[132:135], v[156:159], v[0:15]
	ds_read_b64_tr_b16 v[156:157], v252 offset:58880
	ds_read_b64_tr_b16 v[158:159], v252 offset:60928
	v_exp_f32_e32 v105, v105
	v_exp_f32_e32 v106, v106
	v_exp_f32_e32 v107, v107
	v_add_f32_e32 v182, v104, v182
	v_mfma_f32_32x32x16_bf16 v[64:79], v[220:223], v[160:163], v[64:79]
	v_add_f32_e32 v182, v105, v182
	v_cvt_pk_bf16_f32 v140, v104, v105
	v_exp_f32_e32 v108, v108
	s_waitcnt lgkmcnt(4)
	v_mfma_f32_32x32x16_bf16 v[48:63], v[136:139], v[144:147], v[48:63]
	ds_read_b64_tr_b16 v[144:145], v252 offset:61440
	ds_read_b64_tr_b16 v[146:147], v252 offset:63488
	v_exp_f32_e32 v109, v109
	v_add_f32_e32 v182, v106, v182
	v_add_f32_e32 v182, v107, v182
	v_cvt_pk_bf16_f32 v141, v106, v107
	v_mfma_f32_32x32x16_bf16 v[32:47], v[136:139], v[148:151], v[32:47]
	ds_read_b64_tr_b16 v[148:149], v252 offset:61952
	ds_read_b64_tr_b16 v[150:151], v252 offset:64000
	v_exp_f32_e32 v110, v110
	v_exp_f32_e32 v111, v111
	v_add_f32_e32 v182, v108, v182
	v_add_f32_e32 v182, v109, v182
	s_waitcnt lgkmcnt(4)
	v_mfma_f32_32x32x16_bf16 v[16:31], v[136:139], v[152:155], v[16:31]
	ds_read_b64_tr_b16 v[152:153], v252 offset:62464
	ds_read_b64_tr_b16 v[154:155], v252 offset:64512
	v_cvt_pk_bf16_f32 v142, v108, v109
	v_cvt_pk_bf16_f32 v143, v110, v111
	v_add_f32_e32 v182, v110, v182
	v_add_f32_e32 v182, v111, v182
	v_mfma_f32_32x32x16_bf16 v[0:15], v[136:139], v[156:159], v[0:15]
	ds_read_b64_tr_b16 v[156:157], v252 offset:62976
	ds_read_b64_tr_b16 v[158:159], v252 offset:65024
	v_exp_f32_e32 v80, v80
	v_exp_f32_e32 v81, v81
	v_exp_f32_e32 v82, v82
	v_exp_f32_e32 v83, v83
	s_waitcnt lgkmcnt(4)
	v_mfma_f32_32x32x16_bf16 v[48:63], v[140:143], v[144:147], v[48:63]
	v_add_f32_e32 v182, v80, v182
	v_add_f32_e32 v182, v81, v182
	v_cvt_pk_bf16_f32 v128, v80, v81
	v_exp_f32_e32 v84, v84
	v_mfma_f32_32x32x16_bf16 v[32:47], v[140:143], v[148:151], v[32:47]
	v_exp_f32_e32 v85, v85
	v_add_f32_e32 v182, v82, v182
	v_add_f32_e32 v182, v83, v182
	v_cvt_pk_bf16_f32 v129, v82, v83
	s_waitcnt lgkmcnt(0)
	v_mfma_f32_32x32x16_bf16 v[16:31], v[140:143], v[152:155], v[16:31]
	v_exp_f32_e32 v86, v86
	v_exp_f32_e32 v87, v87
	v_add_f32_e32 v182, v84, v182
	v_add_f32_e32 v182, v85, v182
	v_mfma_f32_32x32x16_bf16 v[0:15], v[140:143], v[156:159], v[0:15]
	v_cvt_pk_bf16_f32 v130, v84, v85
	v_cvt_pk_bf16_f32 v131, v86, v87
	v_add_f32_e32 v182, v86, v182
	v_add_f32_e32 v182, v87, v182
	s_add_i32 s54, s54, 1
	s_branch .Lsym_loop
